# non-temporal (nt) hint on the f32 weight loads of the A-phase idle-workgroup conversions (read-once stream no longer evicts GEMM operands from L2)
# speedup vs baseline: 1.0096x; 1.0039x over previous
.LBB0_213:
	s_mul_hi_i32 s0, s11, 0x22b63cbf
	s_lshr_b32 s1, s0, 31
	s_ashr_i32 s0, s0, 10
	s_add_i32 s0, s0, s1
	s_mul_i32 s1, s0, 0xffffe280
	s_add_i32 s8, s11, s1
	s_ashr_i32 s1, s0, 31
	s_mul_i32 s3, s0, 0x1d80000
	v_readlane_b32 s4, v251, 32
	s_mul_hi_i32 s2, s0, 0x1d80000
	s_add_u32 s13, s4, s3
	v_readlane_b32 s3, v251, 33
	s_addc_u32 s12, s3, s2
	s_cmpk_gt_i32 s8, 0x8ff
	s_mov_b64 s[2:3], -1
	s_cbranch_scc0 .LBB0_231
	s_cmpk_gt_u32 s8, 0x9ff
	s_cbranch_scc0 .LBB0_228
	s_cmpk_gt_u32 s8, 0xaff
	s_cbranch_scc0 .LBB0_225
	s_cmpk_gt_u32 s8, 0xcff
	s_cbranch_scc0 .LBB0_222
	s_cmpk_gt_u32 s8, 0x17ff
	s_cbranch_scc0 .LBB0_219
	s_mul_i32 s2, s0, 0xffffc500
	s_add_i32 s2, s10, s2
	s_addk_i32 s2, 0xe200
	v_readlane_b32 s24, v254, 54
	s_and_b32 s3, s2, 0x7fffffc0
	s_and_b32 s2, s5, 0x3e0
	s_mul_i32 s9, s0, 0xb00000
	v_readlane_b32 s26, v254, 56
	s_mul_hi_i32 s4, s0, 0xb00000
	v_readlane_b32 s27, v254, 57
	s_add_u32 s9, s26, s9
	s_addc_u32 s4, s27, s4
	s_lshl_b32 s14, s2, 2
	v_add_u32_e32 v20, s3, v1
	s_add_u32 s14, s9, s14
	s_addc_u32 s15, s4, 0
	v_ashrrev_i32_e32 v21, 31, v20
	v_lshl_add_u64 v[22:23], s[14:15], 0, v[14:15]
	v_lshlrev_b64 v[20:21], 12, v[20:21]
	v_lshl_add_u64 v[20:21], v[22:23], 0, v[20:21]
	s_movk_i32 s4, 0x2000
	v_add_co_u32_e32 v22, vcc, s4, v20
	s_movk_i32 s4, 0x4000
	s_nop 0
	v_addc_co_u32_e32 v23, vcc, 0, v21, vcc
	v_add_co_u32_e32 v24, vcc, s4, v20
	s_movk_i32 s4, 0x6000
	s_nop 0
	v_addc_co_u32_e32 v25, vcc, 0, v21, vcc
	v_add_co_u32_e32 v26, vcc, s4, v20
	s_mov_b32 s4, 0xa000
	s_nop 0
	v_addc_co_u32_e32 v27, vcc, 0, v21, vcc
	v_add_co_u32_e32 v28, vcc, s66, v20
	s_lshl_b32 s3, s3, 1
	s_nop 0
	v_addc_co_u32_e32 v29, vcc, 0, v21, vcc
	v_add_co_u32_e32 v30, vcc, s4, v20
	s_mov_b32 s4, 0xc000
	s_nop 0
	v_addc_co_u32_e32 v31, vcc, 0, v21, vcc
	v_add_co_u32_e32 v32, vcc, s4, v20
	s_mov_b32 s4, 0xe000
	s_nop 0
	v_addc_co_u32_e32 v33, vcc, 0, v21, vcc
	v_add_co_u32_e32 v34, vcc, s4, v20
	s_mov_b32 s4, 0x12000
	s_nop 0
	v_addc_co_u32_e32 v35, vcc, 0, v21, vcc
	global_load_dword v3, v[20:21], off nt
	global_load_dword v19, v[22:23], off nt
	global_load_dword v38, v[24:25], off nt
	global_load_dword v39, v[26:27], off nt
	global_load_dword v40, v[28:29], off nt
	global_load_dword v41, v[30:31], off nt
	global_load_dword v42, v[32:33], off nt
	global_load_dword v43, v[34:35], off nt
	v_add_co_u32_e32 v22, vcc, s67, v20
	s_add_u32 s14, s13, s3
	s_nop 0
	v_addc_co_u32_e32 v23, vcc, 0, v21, vcc
	v_add_co_u32_e32 v24, vcc, s4, v20
	s_mov_b32 s4, 0x14000
	s_nop 0
	v_addc_co_u32_e32 v25, vcc, 0, v21, vcc
	v_add_co_u32_e32 v26, vcc, s4, v20
	s_mov_b32 s4, 0x16000
	s_nop 0
	v_addc_co_u32_e32 v27, vcc, 0, v21, vcc
	v_add_co_u32_e32 v28, vcc, s4, v20
	s_mov_b32 s4, 0x1a000
	s_nop 0
	v_addc_co_u32_e32 v29, vcc, 0, v21, vcc
	v_add_co_u32_e32 v30, vcc, s68, v20
	s_addc_u32 s15, s12, 0
	s_nop 0
	v_addc_co_u32_e32 v31, vcc, 0, v21, vcc
	v_add_co_u32_e32 v32, vcc, s4, v20
	s_mov_b32 s4, 0x1c000
	s_nop 0
	v_addc_co_u32_e32 v33, vcc, 0, v21, vcc
	v_add_co_u32_e32 v34, vcc, s4, v20
	s_mov_b32 s4, 0x1e000
	s_nop 0
	v_addc_co_u32_e32 v35, vcc, 0, v21, vcc
	v_add_co_u32_e32 v36, vcc, s4, v20
	s_mov_b32 s4, 0x20000
	s_nop 0
	v_addc_co_u32_e32 v37, vcc, 0, v21, vcc
	global_load_dword v44, v[22:23], off nt
	global_load_dword v45, v[24:25], off nt
	global_load_dword v46, v[26:27], off nt
	global_load_dword v47, v[28:29], off nt
	global_load_dword v48, v[30:31], off nt
	global_load_dword v49, v[32:33], off nt
	global_load_dword v50, v[34:35], off nt
	global_load_dword v51, v[36:37], off nt
	v_add_co_u32_e32 v22, vcc, s4, v20
	s_mov_b32 s4, 0x22000
	s_nop 0
	v_addc_co_u32_e32 v23, vcc, 0, v21, vcc
	v_add_co_u32_e32 v24, vcc, s4, v20
	s_mov_b32 s4, 0x24000
	s_nop 0
	v_addc_co_u32_e32 v25, vcc, 0, v21, vcc
	v_add_co_u32_e32 v26, vcc, s4, v20
	s_mov_b32 s4, 0x26000
	s_nop 0
	v_addc_co_u32_e32 v27, vcc, 0, v21, vcc
	v_add_co_u32_e32 v28, vcc, s4, v20
	s_mov_b32 s4, 0x28000
	s_nop 0
	v_addc_co_u32_e32 v29, vcc, 0, v21, vcc
	v_add_co_u32_e32 v30, vcc, s4, v20
	s_mov_b32 s4, 0x2a000
	s_nop 0
	v_addc_co_u32_e32 v31, vcc, 0, v21, vcc
	v_add_co_u32_e32 v32, vcc, s4, v20
	s_mov_b32 s4, 0x2c000
	s_nop 0
	v_addc_co_u32_e32 v33, vcc, 0, v21, vcc
	v_add_co_u32_e32 v34, vcc, s4, v20
	s_mov_b32 s4, 0x2e000
	s_nop 0
	v_addc_co_u32_e32 v35, vcc, 0, v21, vcc
	v_add_co_u32_e32 v36, vcc, s4, v20
	s_mov_b32 s4, 0x30000
	s_nop 0
	v_addc_co_u32_e32 v37, vcc, 0, v21, vcc
	global_load_dword v52, v[22:23], off nt
	global_load_dword v53, v[24:25], off nt
	global_load_dword v54, v[26:27], off nt
	global_load_dword v55, v[28:29], off nt
	global_load_dword v56, v[30:31], off nt
	global_load_dword v57, v[32:33], off nt
	global_load_dword v58, v[34:35], off nt
	s_nop 0
	global_load_dword v36, v[36:37], off nt
	v_add_co_u32_e32 v22, vcc, s4, v20
	s_mov_b32 s4, 0x32000
	s_nop 0
	v_addc_co_u32_e32 v23, vcc, 0, v21, vcc
	v_add_co_u32_e32 v24, vcc, s4, v20
	s_mov_b32 s4, 0x34000
	s_nop 0
	v_addc_co_u32_e32 v25, vcc, 0, v21, vcc
	v_add_co_u32_e32 v26, vcc, s4, v20
	s_mov_b32 s4, 0x36000
	s_nop 0
	v_addc_co_u32_e32 v27, vcc, 0, v21, vcc
	v_add_co_u32_e32 v28, vcc, s4, v20
	s_mov_b32 s4, 0x38000
	s_nop 0
	v_addc_co_u32_e32 v29, vcc, 0, v21, vcc
	v_add_co_u32_e32 v30, vcc, s4, v20
	s_mov_b32 s4, 0x3a000
	s_nop 0
	v_addc_co_u32_e32 v31, vcc, 0, v21, vcc
	v_add_co_u32_e32 v32, vcc, s4, v20
	s_mov_b32 s4, 0x3c000
	s_nop 0
	v_addc_co_u32_e32 v33, vcc, 0, v21, vcc
	v_add_co_u32_e32 v34, vcc, s4, v20
	s_mov_b32 s4, 0x3e000
	s_nop 0
	v_addc_co_u32_e32 v35, vcc, 0, v21, vcc
	v_add_co_u32_e32 v20, vcc, s4, v20
	s_movk_i32 s3, 0x7fff
	s_nop 0
	v_addc_co_u32_e32 v21, vcc, 0, v21, vcc
	global_load_dword v22, v[22:23], off nt
	s_nop 0
	global_load_dword v23, v[24:25], off nt
	s_nop 0
	global_load_dword v24, v[26:27], off nt
	global_load_dword v25, v[28:29], off nt
	s_nop 0
	global_load_dword v26, v[30:31], off nt
	global_load_dword v27, v[32:33], off nt
	global_load_dword v28, v[34:35], off nt
	s_nop 0
	global_load_dword v20, v[20:21], off nt
	s_waitcnt vmcnt(30)
	ds_write2_b32 v4, v3, v19 offset1:66
	s_waitcnt vmcnt(28)
	ds_write2_b32 v4, v38, v39 offset0:132 offset1:198
	s_waitcnt vmcnt(26)
	ds_write2_b32 v10, v40, v41 offset0:8 offset1:74
	s_waitcnt vmcnt(24)
	ds_write2_b32 v10, v42, v43 offset0:140 offset1:206
	s_waitcnt vmcnt(22)
	ds_write2_b32 v11, v44, v45 offset0:16 offset1:82
	s_waitcnt vmcnt(20)
	ds_write2_b32 v11, v46, v47 offset0:148 offset1:214
	s_waitcnt vmcnt(18)
	ds_write2_b32 v12, v48, v49 offset0:24 offset1:90
	s_waitcnt vmcnt(16)
	ds_write2_b32 v12, v50, v51 offset0:156 offset1:222
	s_waitcnt vmcnt(14)
	ds_write2_b32 v13, v52, v53 offset0:32 offset1:98
	s_waitcnt vmcnt(12)
	ds_write2_b32 v13, v54, v55 offset0:164 offset1:230
	s_waitcnt vmcnt(10)
	ds_write2_b32 v16, v56, v57 offset0:40 offset1:106
	s_waitcnt vmcnt(8)
	ds_write2_b32 v16, v58, v36 offset0:172 offset1:238
	s_waitcnt vmcnt(6)
	ds_write2_b32 v17, v22, v23 offset0:48 offset1:114
	s_waitcnt vmcnt(4)
	ds_write2_b32 v17, v24, v25 offset0:180 offset1:246
	s_waitcnt vmcnt(2)
	ds_write2_b32 v18, v26, v27 offset0:56 offset1:122
	s_waitcnt vmcnt(0)
	ds_write2_b32 v18, v28, v20 offset0:188 offset1:254
	s_waitcnt lgkmcnt(0)
	ds_read2_b32 v[24:25], v6 offset1:8
	ds_read2_b32 v[28:29], v6 offset0:33 offset1:41
	ds_read2_b32 v[30:31], v6 offset0:66 offset1:74
	v_mov_b32_e32 v3, v15
	ds_read2_b32 v[32:33], v6 offset0:99 offset1:107
	v_lshl_add_u64 v[20:21], s[14:15], 0, v[2:3]
	s_waitcnt lgkmcnt(3)
	v_bfe_u32 v3, v24, 16, 1
	v_add3_u32 v3, v24, v3, s3
	s_waitcnt lgkmcnt(2)
	v_bfe_u32 v19, v28, 16, 1
	ds_read2_b32 v[34:35], v6 offset0:132 offset1:140
	s_mov_b64 s[14:15], 0x1800000
	v_lshrrev_b32_e32 v3, 16, v3
	v_add3_u32 v19, v28, v19, s3
	ds_read2_b32 v[36:37], v6 offset0:165 offset1:173
	v_lshl_add_u64 v[26:27], v[20:21], 0, s[14:15]
	v_and_or_b32 v20, v19, s69, v3
	s_waitcnt lgkmcnt(3)
	v_bfe_u32 v3, v30, 16, 1
	v_add3_u32 v3, v30, v3, s3
	s_waitcnt lgkmcnt(2)
	v_bfe_u32 v19, v32, 16, 1
	ds_read2_b32 v[38:39], v6 offset0:198 offset1:206
	v_lshrrev_b32_e32 v3, 16, v3
	v_add3_u32 v19, v32, v19, s3
	ds_read2_b32 v[40:41], v6 offset0:231 offset1:239
	v_and_or_b32 v21, v19, s69, v3
	s_waitcnt lgkmcnt(3)
	v_bfe_u32 v3, v34, 16, 1
	v_add3_u32 v3, v34, v3, s3
	s_waitcnt lgkmcnt(2)
	v_bfe_u32 v19, v36, 16, 1
	v_lshrrev_b32_e32 v3, 16, v3
	v_add3_u32 v19, v36, v19, s3
	v_and_or_b32 v22, v19, s69, v3
	s_waitcnt lgkmcnt(1)
	v_bfe_u32 v3, v38, 16, 1
	v_add3_u32 v3, v38, v3, s3
	s_waitcnt lgkmcnt(0)
	v_bfe_u32 v19, v40, 16, 1
	v_lshrrev_b32_e32 v3, 16, v3
	v_add3_u32 v19, v40, v19, s3
	v_and_or_b32 v23, v19, s69, v3
	v_add_u32_e32 v3, s2, v5
	v_mad_i64_i32 v[42:43], s[14:15], v3, s73, v[26:27]
	v_bfe_u32 v3, v25, 16, 1
	v_add3_u32 v3, v25, v3, s3
	v_bfe_u32 v19, v29, 16, 1
	v_lshrrev_b32_e32 v3, 16, v3
	v_add3_u32 v19, v29, v19, s3
	global_store_dwordx4 v[42:43], v[20:23], off
	ds_read2_b32 v[24:25], v6 offset0:16 offset1:24
	v_readlane_b32 s25, v254, 55
	v_and_or_b32 v20, v19, s69, v3
	v_bfe_u32 v3, v31, 16, 1
	v_add3_u32 v3, v31, v3, s3
	v_bfe_u32 v19, v33, 16, 1
	v_lshrrev_b32_e32 v3, 16, v3
	v_add3_u32 v19, v33, v19, s3
	v_and_or_b32 v21, v19, s69, v3
	v_bfe_u32 v3, v35, 16, 1
	v_add3_u32 v3, v35, v3, s3
	v_bfe_u32 v19, v37, 16, 1
	v_lshrrev_b32_e32 v3, 16, v3
	v_add3_u32 v19, v37, v19, s3
	v_and_or_b32 v22, v19, s69, v3
	v_bfe_u32 v3, v39, 16, 1
	v_add3_u32 v3, v39, v3, s3
	v_bfe_u32 v19, v41, 16, 1
	v_lshrrev_b32_e32 v3, 16, v3
	v_add3_u32 v19, v41, v19, s3
	v_and_or_b32 v23, v19, s69, v3
	v_add_u32_e32 v3, s2, v7
	v_mad_i64_i32 v[28:29], s[14:15], v3, s73, v[26:27]
	global_store_dwordx4 v[28:29], v[20:23], off
	ds_read2_b32 v[28:29], v6 offset0:49 offset1:57
	ds_read2_b32 v[30:31], v6 offset0:82 offset1:90
	ds_read2_b32 v[32:33], v6 offset0:115 offset1:123
	s_waitcnt lgkmcnt(3)
	v_bfe_u32 v3, v24, 16, 1
	v_add3_u32 v3, v24, v3, s3
	s_waitcnt lgkmcnt(2)
	v_bfe_u32 v19, v28, 16, 1
	ds_read2_b32 v[34:35], v6 offset0:148 offset1:156
	v_lshrrev_b32_e32 v3, 16, v3
	v_add3_u32 v19, v28, v19, s3
	ds_read2_b32 v[36:37], v6 offset0:181 offset1:189
	v_and_or_b32 v20, v19, s69, v3
	s_waitcnt lgkmcnt(3)
	v_bfe_u32 v3, v30, 16, 1
	v_add3_u32 v3, v30, v3, s3
	s_waitcnt lgkmcnt(2)
	v_bfe_u32 v19, v32, 16, 1
	ds_read2_b32 v[38:39], v6 offset0:214 offset1:222
	v_lshrrev_b32_e32 v3, 16, v3
	v_add3_u32 v19, v32, v19, s3
	ds_read2_b32 v[40:41], v6 offset0:247 offset1:255
	v_and_or_b32 v21, v19, s69, v3
	s_waitcnt lgkmcnt(3)
	v_bfe_u32 v3, v34, 16, 1
	v_add3_u32 v3, v34, v3, s3
	s_waitcnt lgkmcnt(2)
	v_bfe_u32 v19, v36, 16, 1
	v_lshrrev_b32_e32 v3, 16, v3
	v_add3_u32 v19, v36, v19, s3
	v_and_or_b32 v22, v19, s69, v3
	s_waitcnt lgkmcnt(1)
	v_bfe_u32 v3, v38, 16, 1
	v_add3_u32 v3, v38, v3, s3
	s_waitcnt lgkmcnt(0)
	v_bfe_u32 v19, v40, 16, 1
	v_lshrrev_b32_e32 v3, 16, v3
	v_add3_u32 v19, v40, v19, s3
	v_and_or_b32 v23, v19, s69, v3
	v_add_u32_e32 v3, s2, v8
	v_mad_i64_i32 v[42:43], s[14:15], v3, s73, v[26:27]
	v_bfe_u32 v3, v25, 16, 1
	v_add3_u32 v3, v25, v3, s3
	v_bfe_u32 v19, v29, 16, 1
	v_lshrrev_b32_e32 v3, 16, v3
	v_add3_u32 v19, v29, v19, s3
	global_store_dwordx4 v[42:43], v[20:23], off
	s_nop 1
	v_and_or_b32 v20, v19, s69, v3
	v_bfe_u32 v3, v31, 16, 1
	v_add3_u32 v3, v31, v3, s3
	v_bfe_u32 v19, v33, 16, 1
	v_lshrrev_b32_e32 v3, 16, v3
	v_add3_u32 v19, v33, v19, s3
	v_and_or_b32 v21, v19, s69, v3
	v_bfe_u32 v3, v35, 16, 1
	v_add3_u32 v3, v35, v3, s3
	v_bfe_u32 v19, v37, 16, 1
	v_lshrrev_b32_e32 v3, 16, v3
	v_add3_u32 v19, v37, v19, s3
	v_and_or_b32 v22, v19, s69, v3
	v_bfe_u32 v3, v39, 16, 1
	v_add3_u32 v3, v39, v3, s3
	v_bfe_u32 v19, v41, 16, 1
	v_lshrrev_b32_e32 v3, 16, v3
	v_add3_u32 v19, v41, v19, s3
	v_and_or_b32 v23, v19, s69, v3
	v_add_u32_e32 v3, s2, v9
	v_mad_i64_i32 v[24:25], s[2:3], v3, s73, v[26:27]
	global_store_dwordx4 v[24:25], v[20:23], off
	s_waitcnt lgkmcnt(0)
	s_mov_b64 s[2:3], 0
.LBB0_219:
	s_andn2_b64 vcc, exec, s[2:3]
	s_cbranch_vccnz .LBB0_221
	s_add_i32 s2, s8, 0xf300
	s_and_b32 s3, s2, 0xffff
	s_mul_i32 s3, s3, 0xba2f
	s_lshr_b32 s3, s3, 23
	s_mul_i32 s4, s3, 0xb0
	s_sub_i32 s2, s2, s4
	s_lshl_b32 s4, s2, 5
	v_readlane_b32 s40, v254, 31
	s_and_b32 s9, s4, 0xffe0
	s_mul_i32 s15, s0, 0x1600000
	v_readlane_b32 s44, v254, 35
	s_mul_hi_i32 s14, s0, 0x1600000
	v_readlane_b32 s45, v254, 36
	s_add_u32 s15, s44, s15
	s_addc_u32 s17, s45, s14
	s_and_b32 s2, s2, 0xffff
	s_cmpk_gt_u32 s2, 0x57
	s_cselect_b32 s2, 0xfffff500, 0
	s_cselect_b32 s14, 0x80, 0
	s_add_i32 s2, s2, s9
	s_lshl_b32 s2, s2, 1
	s_and_b32 s4, s4, 0x60
	s_and_b32 s2, s2, 0x7fffff00
	s_or_b32 s4, s4, s14
	s_or_b32 s2, s4, s2
	s_lshl_b32 s4, s9, 2
	s_add_u32 s14, s15, s4
	v_lshl_add_u32 v3, s3, 6, v1
	s_addc_u32 s15, s17, 0
	v_lshl_add_u64 v[20:21], s[14:15], 0, v[14:15]
	s_movk_i32 s4, 0x5800
	v_add_u32_e32 v19, 2, v3
	v_mad_i64_i32 v[24:25], s[14:15], v19, s4, v[20:21]
	v_add_u32_e32 v19, 4, v3
	v_mad_i64_i32 v[26:27], s[14:15], v19, s4, v[20:21]
	v_add_u32_e32 v19, 6, v3
	v_mad_i64_i32 v[28:29], s[14:15], v19, s4, v[20:21]
	v_add_u32_e32 v19, 8, v3
	v_mad_i64_i32 v[30:31], s[14:15], v19, s4, v[20:21]
	v_add_u32_e32 v19, 10, v3
	v_mad_i64_i32 v[32:33], s[14:15], v19, s4, v[20:21]
	v_add_u32_e32 v19, 12, v3
	v_mad_i64_i32 v[34:35], s[14:15], v19, s4, v[20:21]
	v_add_u32_e32 v19, 14, v3
	v_mad_i64_i32 v[22:23], s[14:15], v3, s4, v[20:21]
	v_mad_i64_i32 v[36:37], s[14:15], v19, s4, v[20:21]
	global_load_dword v19, v[22:23], off nt
	global_load_dword v38, v[24:25], off nt
	global_load_dword v39, v[26:27], off nt
	global_load_dword v40, v[28:29], off nt
	global_load_dword v41, v[30:31], off nt
	global_load_dword v42, v[32:33], off nt
	global_load_dword v43, v[34:35], off nt
	global_load_dword v44, v[36:37], off nt
	v_add_u32_e32 v22, 16, v3
	v_add_u32_e32 v24, 18, v3
	v_add_u32_e32 v26, 20, v3
	v_add_u32_e32 v28, 22, v3
	v_add_u32_e32 v30, 24, v3
	v_add_u32_e32 v32, 26, v3
	v_add_u32_e32 v34, 28, v3
	v_add_u32_e32 v36, 30, v3
	v_mad_i64_i32 v[22:23], s[14:15], v22, s4, v[20:21]
	v_mad_i64_i32 v[24:25], s[14:15], v24, s4, v[20:21]
	v_mad_i64_i32 v[26:27], s[14:15], v26, s4, v[20:21]
	v_mad_i64_i32 v[28:29], s[14:15], v28, s4, v[20:21]
	v_mad_i64_i32 v[30:31], s[14:15], v30, s4, v[20:21]
	v_mad_i64_i32 v[32:33], s[14:15], v32, s4, v[20:21]
	v_mad_i64_i32 v[34:35], s[14:15], v34, s4, v[20:21]
	v_mad_i64_i32 v[36:37], s[14:15], v36, s4, v[20:21]
	global_load_dword v45, v[22:23], off nt
	global_load_dword v46, v[24:25], off nt
	global_load_dword v47, v[26:27], off nt
	global_load_dword v48, v[28:29], off nt
	global_load_dword v49, v[30:31], off nt
	global_load_dword v50, v[32:33], off nt
	global_load_dword v51, v[34:35], off nt
	global_load_dword v52, v[36:37], off nt
	v_add_u32_e32 v22, 32, v3
	v_add_u32_e32 v24, 34, v3
	v_add_u32_e32 v26, 36, v3
	v_add_u32_e32 v28, 38, v3
	v_add_u32_e32 v30, 40, v3
	v_add_u32_e32 v32, 42, v3
	v_add_u32_e32 v34, 44, v3
	v_add_u32_e32 v36, 46, v3
	v_mad_i64_i32 v[22:23], s[14:15], v22, s4, v[20:21]
	v_mad_i64_i32 v[24:25], s[14:15], v24, s4, v[20:21]
	v_mad_i64_i32 v[26:27], s[14:15], v26, s4, v[20:21]
	v_mad_i64_i32 v[28:29], s[14:15], v28, s4, v[20:21]
	v_mad_i64_i32 v[30:31], s[14:15], v30, s4, v[20:21]
	v_mad_i64_i32 v[32:33], s[14:15], v32, s4, v[20:21]
	v_mad_i64_i32 v[34:35], s[14:15], v34, s4, v[20:21]
	v_mad_i64_i32 v[36:37], s[14:15], v36, s4, v[20:21]
	global_load_dword v53, v[22:23], off nt
	global_load_dword v54, v[24:25], off nt
	global_load_dword v55, v[26:27], off nt
	global_load_dword v56, v[28:29], off nt
	global_load_dword v57, v[30:31], off nt
	global_load_dword v58, v[32:33], off nt
	global_load_dword v59, v[34:35], off nt
	s_nop 0
	global_load_dword v36, v[36:37], off nt
	v_add_u32_e32 v22, 48, v3
	v_add_u32_e32 v24, 50, v3
	v_add_u32_e32 v26, 52, v3
	v_add_u32_e32 v28, 54, v3
	v_add_u32_e32 v30, 56, v3
	v_add_u32_e32 v32, 58, v3
	v_add_u32_e32 v34, 60, v3
	v_add_u32_e32 v3, 62, v3
	v_mad_i64_i32 v[22:23], s[14:15], v22, s4, v[20:21]
	v_mad_i64_i32 v[24:25], s[14:15], v24, s4, v[20:21]
	v_mad_i64_i32 v[26:27], s[14:15], v26, s4, v[20:21]
	v_mad_i64_i32 v[28:29], s[14:15], v28, s4, v[20:21]
	v_mad_i64_i32 v[30:31], s[14:15], v30, s4, v[20:21]
	v_mad_i64_i32 v[32:33], s[14:15], v32, s4, v[20:21]
	v_mad_i64_i32 v[34:35], s[14:15], v34, s4, v[20:21]
	v_mad_i64_i32 v[20:21], s[14:15], v3, s4, v[20:21]
	global_load_dword v3, v[22:23], off nt
	s_nop 0
	global_load_dword v22, v[24:25], off nt
	global_load_dword v23, v[26:27], off nt
	s_nop 0
	global_load_dword v24, v[28:29], off nt
	global_load_dword v25, v[30:31], off nt
	global_load_dword v26, v[32:33], off nt
	global_load_dword v27, v[34:35], off nt
	s_nop 0
	global_load_dword v20, v[20:21], off nt
	s_waitcnt vmcnt(30)
	ds_write2_b32 v4, v19, v38 offset1:66
	s_waitcnt vmcnt(28)
	ds_write2_b32 v4, v39, v40 offset0:132 offset1:198
	s_waitcnt vmcnt(26)
	ds_write2_b32 v10, v41, v42 offset0:8 offset1:74
	s_waitcnt vmcnt(24)
	ds_write2_b32 v10, v43, v44 offset0:140 offset1:206
	s_waitcnt vmcnt(22)
	ds_write2_b32 v11, v45, v46 offset0:16 offset1:82
	s_waitcnt vmcnt(20)
	ds_write2_b32 v11, v47, v48 offset0:148 offset1:214
	s_waitcnt vmcnt(18)
	ds_write2_b32 v12, v49, v50 offset0:24 offset1:90
	s_waitcnt vmcnt(16)
	ds_write2_b32 v12, v51, v52 offset0:156 offset1:222
	s_waitcnt vmcnt(14)
	ds_write2_b32 v13, v53, v54 offset0:32 offset1:98
	s_waitcnt vmcnt(12)
	ds_write2_b32 v13, v55, v56 offset0:164 offset1:230
	s_waitcnt vmcnt(10)
	ds_write2_b32 v16, v57, v58 offset0:40 offset1:106
	s_waitcnt vmcnt(8)
	ds_write2_b32 v16, v59, v36 offset0:172 offset1:238
	s_waitcnt vmcnt(6)
	ds_write2_b32 v17, v3, v22 offset0:48 offset1:114
	s_waitcnt vmcnt(4)
	ds_write2_b32 v17, v23, v24 offset0:180 offset1:246
	s_waitcnt vmcnt(2)
	ds_write2_b32 v18, v25, v26 offset0:56 offset1:122
	s_waitcnt vmcnt(0)
	ds_write2_b32 v18, v27, v20 offset0:188 offset1:254
	s_waitcnt lgkmcnt(0)
	ds_read2_b32 v[24:25], v6 offset1:8
	ds_read2_b32 v[28:29], v6 offset0:33 offset1:41
	s_lshl_b32 s3, s3, 7
	s_add_u32 s14, s13, s3
	ds_read2_b32 v[30:31], v6 offset0:66 offset1:74
	s_addc_u32 s15, s12, 0
	v_mov_b32_e32 v3, v15
	ds_read2_b32 v[32:33], v6 offset0:99 offset1:107
	v_lshl_add_u64 v[20:21], s[14:15], 0, v[2:3]
	s_waitcnt lgkmcnt(3)
	v_bfe_u32 v3, v24, 16, 1
	s_movk_i32 s3, 0x7fff
	v_add3_u32 v3, v24, v3, s3
	s_waitcnt lgkmcnt(2)
	v_bfe_u32 v19, v28, 16, 1
	ds_read2_b32 v[34:35], v6 offset0:132 offset1:140
	s_mov_b64 s[14:15], 0xd00000
	v_lshrrev_b32_e32 v3, 16, v3
	v_add3_u32 v19, v28, v19, s3
	ds_read2_b32 v[36:37], v6 offset0:165 offset1:173
	v_lshl_add_u64 v[26:27], v[20:21], 0, s[14:15]
	v_and_or_b32 v20, v19, s69, v3
	s_waitcnt lgkmcnt(3)
	v_bfe_u32 v3, v30, 16, 1
	v_add3_u32 v3, v30, v3, s3
	s_waitcnt lgkmcnt(2)
	v_bfe_u32 v19, v32, 16, 1
	ds_read2_b32 v[38:39], v6 offset0:198 offset1:206
	v_lshrrev_b32_e32 v3, 16, v3
	v_add3_u32 v19, v32, v19, s3
	ds_read2_b32 v[40:41], v6 offset0:231 offset1:239
	v_and_or_b32 v21, v19, s69, v3
	s_waitcnt lgkmcnt(3)
	v_bfe_u32 v3, v34, 16, 1
	v_add3_u32 v3, v34, v3, s3
	s_waitcnt lgkmcnt(2)
	v_bfe_u32 v19, v36, 16, 1
	v_lshrrev_b32_e32 v3, 16, v3
	v_add3_u32 v19, v36, v19, s3
	v_and_or_b32 v22, v19, s69, v3
	s_waitcnt lgkmcnt(1)
	v_bfe_u32 v3, v38, 16, 1
	v_add3_u32 v3, v38, v3, s3
	s_waitcnt lgkmcnt(0)
	v_bfe_u32 v19, v40, 16, 1
	v_lshrrev_b32_e32 v3, 16, v3
	v_add3_u32 v19, v40, v19, s3
	v_add_u32_e32 v42, s2, v5
	v_and_or_b32 v23, v19, s69, v3
	v_ashrrev_i32_e32 v43, 31, v42
	v_bfe_u32 v3, v25, 16, 1
	v_lshlrev_b64 v[42:43], 11, v[42:43]
	v_add3_u32 v3, v25, v3, s3
	v_bfe_u32 v19, v29, 16, 1
	v_lshl_add_u64 v[42:43], v[26:27], 0, v[42:43]
	v_lshrrev_b32_e32 v3, 16, v3
	v_add3_u32 v19, v29, v19, s3
	global_store_dwordx4 v[42:43], v[20:23], off
	v_add_u32_e32 v24, s2, v7
	v_ashrrev_i32_e32 v25, 31, v24
	v_and_or_b32 v20, v19, s69, v3
	v_bfe_u32 v3, v31, 16, 1
	v_add3_u32 v3, v31, v3, s3
	v_bfe_u32 v19, v33, 16, 1
	v_lshrrev_b32_e32 v3, 16, v3
	v_add3_u32 v19, v33, v19, s3
	v_and_or_b32 v21, v19, s69, v3
	v_bfe_u32 v3, v35, 16, 1
	v_add3_u32 v3, v35, v3, s3
	v_bfe_u32 v19, v37, 16, 1
	v_lshrrev_b32_e32 v3, 16, v3
	v_add3_u32 v19, v37, v19, s3
	v_and_or_b32 v22, v19, s69, v3
	v_bfe_u32 v3, v39, 16, 1
	v_add3_u32 v3, v39, v3, s3
	v_bfe_u32 v19, v41, 16, 1
	v_lshrrev_b32_e32 v3, 16, v3
	v_add3_u32 v19, v41, v19, s3
	v_lshlrev_b64 v[24:25], 11, v[24:25]
	v_and_or_b32 v23, v19, s69, v3
	ds_read2_b32 v[28:29], v6 offset0:16 offset1:24
	v_lshl_add_u64 v[24:25], v[26:27], 0, v[24:25]
	global_store_dwordx4 v[24:25], v[20:23], off
	ds_read2_b32 v[24:25], v6 offset0:49 offset1:57
	ds_read2_b32 v[30:31], v6 offset0:82 offset1:90
	ds_read2_b32 v[32:33], v6 offset0:115 offset1:123
	s_waitcnt lgkmcnt(3)
	v_bfe_u32 v3, v28, 16, 1
	v_add3_u32 v3, v28, v3, s3
	s_waitcnt lgkmcnt(2)
	v_bfe_u32 v19, v24, 16, 1
	ds_read2_b32 v[34:35], v6 offset0:148 offset1:156
	v_lshrrev_b32_e32 v3, 16, v3
	v_add3_u32 v19, v24, v19, s3
	ds_read2_b32 v[36:37], v6 offset0:181 offset1:189
	v_and_or_b32 v20, v19, s69, v3
	s_waitcnt lgkmcnt(3)
	v_bfe_u32 v3, v30, 16, 1
	v_add3_u32 v3, v30, v3, s3
	s_waitcnt lgkmcnt(2)
	v_bfe_u32 v19, v32, 16, 1
	ds_read2_b32 v[38:39], v6 offset0:214 offset1:222
	v_lshrrev_b32_e32 v3, 16, v3
	v_add3_u32 v19, v32, v19, s3
	ds_read2_b32 v[40:41], v6 offset0:247 offset1:255
	v_and_or_b32 v21, v19, s69, v3
	s_waitcnt lgkmcnt(3)
	v_bfe_u32 v3, v34, 16, 1
	v_add3_u32 v3, v34, v3, s3
	s_waitcnt lgkmcnt(2)
	v_bfe_u32 v19, v36, 16, 1
	v_lshrrev_b32_e32 v3, 16, v3
	v_add3_u32 v19, v36, v19, s3
	v_and_or_b32 v22, v19, s69, v3
	s_waitcnt lgkmcnt(1)
	v_bfe_u32 v3, v38, 16, 1
	v_add3_u32 v3, v38, v3, s3
	s_waitcnt lgkmcnt(0)
	v_bfe_u32 v19, v40, 16, 1
	v_lshrrev_b32_e32 v3, 16, v3
	v_add3_u32 v19, v40, v19, s3
	v_add_u32_e32 v42, s2, v8
	v_and_or_b32 v23, v19, s69, v3
	v_ashrrev_i32_e32 v43, 31, v42
	v_bfe_u32 v3, v29, 16, 1
	v_lshlrev_b64 v[42:43], 11, v[42:43]
	v_add3_u32 v3, v29, v3, s3
	v_bfe_u32 v19, v25, 16, 1
	v_lshl_add_u64 v[42:43], v[26:27], 0, v[42:43]
	v_lshrrev_b32_e32 v3, 16, v3
	v_add3_u32 v19, v25, v19, s3
	global_store_dwordx4 v[42:43], v[20:23], off
	v_add_u32_e32 v24, s2, v9
	v_ashrrev_i32_e32 v25, 31, v24
	v_and_or_b32 v20, v19, s69, v3
	v_bfe_u32 v3, v31, 16, 1
	v_add3_u32 v3, v31, v3, s3
	v_bfe_u32 v19, v33, 16, 1
	v_lshrrev_b32_e32 v3, 16, v3
	v_add3_u32 v19, v33, v19, s3
	v_and_or_b32 v21, v19, s69, v3
	v_bfe_u32 v3, v35, 16, 1
	v_add3_u32 v3, v35, v3, s3
	v_bfe_u32 v19, v37, 16, 1
	v_lshrrev_b32_e32 v3, 16, v3
	v_add3_u32 v19, v37, v19, s3
	v_and_or_b32 v22, v19, s69, v3
	v_bfe_u32 v3, v39, 16, 1
	v_add3_u32 v3, v39, v3, s3
	v_bfe_u32 v19, v41, 16, 1
	v_lshrrev_b32_e32 v3, 16, v3
	v_add3_u32 v19, v41, v19, s3
	v_lshlrev_b64 v[24:25], 11, v[24:25]
	v_and_or_b32 v23, v19, s69, v3
	v_lshl_add_u64 v[24:25], v[26:27], 0, v[24:25]
	global_store_dwordx4 v[24:25], v[20:23], off
	s_waitcnt lgkmcnt(0)
	v_readlane_b32 s41, v254, 32
	v_readlane_b32 s42, v254, 33
	v_readlane_b32 s43, v254, 34
	v_readlane_b32 s46, v254, 37
	v_readlane_b32 s47, v254, 38

.LBB0_222:
	s_andn2_b64 vcc, exec, s[2:3]
	s_cbranch_vccnz .LBB0_224
	s_mul_i32 s2, s0, 0xffffc500
	s_add_i32 s2, s10, s2
	s_addk_i32 s2, 0xfc00
	v_readlane_b32 s40, v254, 31
	s_and_b32 s3, s2, 0x7fffffc0
	s_and_b32 s2, s5, 0x3e0
	s_lshl_b64 s[14:15], s[0:1], 22
	v_readlane_b32 s42, v254, 33
	v_readlane_b32 s43, v254, 34
	s_add_u32 s4, s42, s14
	s_addc_u32 s9, s43, s15
	s_lshl_b32 s14, s2, 2
	v_add_u32_e32 v20, s3, v1
	s_add_u32 s14, s4, s14
	s_addc_u32 s15, s9, 0
	v_ashrrev_i32_e32 v21, 31, v20
	v_lshl_add_u64 v[22:23], s[14:15], 0, v[14:15]
	v_lshlrev_b64 v[20:21], 12, v[20:21]
	v_lshl_add_u64 v[20:21], v[22:23], 0, v[20:21]
	s_movk_i32 s4, 0x2000
	v_add_co_u32_e32 v22, vcc, s4, v20
	s_movk_i32 s4, 0x4000
	s_nop 0
	v_addc_co_u32_e32 v23, vcc, 0, v21, vcc
	v_add_co_u32_e32 v24, vcc, s4, v20
	s_movk_i32 s4, 0x6000
	s_nop 0
	v_addc_co_u32_e32 v25, vcc, 0, v21, vcc
	v_add_co_u32_e32 v26, vcc, s4, v20
	s_mov_b32 s4, 0xa000
	s_nop 0
	v_addc_co_u32_e32 v27, vcc, 0, v21, vcc
	v_add_co_u32_e32 v28, vcc, s66, v20
	s_lshl_b32 s3, s3, 1
	s_nop 0
	v_addc_co_u32_e32 v29, vcc, 0, v21, vcc
	v_add_co_u32_e32 v30, vcc, s4, v20
	s_mov_b32 s4, 0xc000
	s_nop 0
	v_addc_co_u32_e32 v31, vcc, 0, v21, vcc
	v_add_co_u32_e32 v32, vcc, s4, v20
	s_mov_b32 s4, 0xe000
	s_nop 0
	v_addc_co_u32_e32 v33, vcc, 0, v21, vcc
	v_add_co_u32_e32 v34, vcc, s4, v20
	s_mov_b32 s4, 0x12000
	s_nop 0
	v_addc_co_u32_e32 v35, vcc, 0, v21, vcc
	global_load_dword v3, v[20:21], off nt
	global_load_dword v19, v[22:23], off nt
	global_load_dword v38, v[24:25], off nt
	global_load_dword v39, v[26:27], off nt
	global_load_dword v40, v[28:29], off nt
	global_load_dword v41, v[30:31], off nt
	global_load_dword v42, v[32:33], off nt
	global_load_dword v43, v[34:35], off nt
	v_add_co_u32_e32 v22, vcc, s67, v20
	s_add_u32 s14, s13, s3
	s_nop 0
	v_addc_co_u32_e32 v23, vcc, 0, v21, vcc
	v_add_co_u32_e32 v24, vcc, s4, v20
	s_mov_b32 s4, 0x14000
	s_nop 0
	v_addc_co_u32_e32 v25, vcc, 0, v21, vcc
	v_add_co_u32_e32 v26, vcc, s4, v20
	s_mov_b32 s4, 0x16000
	s_nop 0
	v_addc_co_u32_e32 v27, vcc, 0, v21, vcc
	v_add_co_u32_e32 v28, vcc, s4, v20
	s_mov_b32 s4, 0x1a000
	s_nop 0
	v_addc_co_u32_e32 v29, vcc, 0, v21, vcc
	v_add_co_u32_e32 v30, vcc, s68, v20
	s_addc_u32 s15, s12, 0
	s_nop 0
	v_addc_co_u32_e32 v31, vcc, 0, v21, vcc
	v_add_co_u32_e32 v32, vcc, s4, v20
	s_mov_b32 s4, 0x1c000
	s_nop 0
	v_addc_co_u32_e32 v33, vcc, 0, v21, vcc
	v_add_co_u32_e32 v34, vcc, s4, v20
	s_mov_b32 s4, 0x1e000
	s_nop 0
	v_addc_co_u32_e32 v35, vcc, 0, v21, vcc
	v_add_co_u32_e32 v36, vcc, s4, v20
	s_mov_b32 s4, 0x20000
	s_nop 0
	v_addc_co_u32_e32 v37, vcc, 0, v21, vcc
	global_load_dword v44, v[22:23], off nt
	global_load_dword v45, v[24:25], off nt
	global_load_dword v46, v[26:27], off nt
	global_load_dword v47, v[28:29], off nt
	global_load_dword v48, v[30:31], off nt
	global_load_dword v49, v[32:33], off nt
	global_load_dword v50, v[34:35], off nt
	global_load_dword v51, v[36:37], off nt
	v_add_co_u32_e32 v22, vcc, s4, v20
	s_mov_b32 s4, 0x22000
	s_nop 0
	v_addc_co_u32_e32 v23, vcc, 0, v21, vcc
	v_add_co_u32_e32 v24, vcc, s4, v20
	s_mov_b32 s4, 0x24000
	s_nop 0
	v_addc_co_u32_e32 v25, vcc, 0, v21, vcc
	v_add_co_u32_e32 v26, vcc, s4, v20
	s_mov_b32 s4, 0x26000
	s_nop 0
	v_addc_co_u32_e32 v27, vcc, 0, v21, vcc
	v_add_co_u32_e32 v28, vcc, s4, v20
	s_mov_b32 s4, 0x28000
	s_nop 0
	v_addc_co_u32_e32 v29, vcc, 0, v21, vcc
	v_add_co_u32_e32 v30, vcc, s4, v20
	s_mov_b32 s4, 0x2a000
	s_nop 0
	v_addc_co_u32_e32 v31, vcc, 0, v21, vcc
	v_add_co_u32_e32 v32, vcc, s4, v20
	s_mov_b32 s4, 0x2c000
	s_nop 0
	v_addc_co_u32_e32 v33, vcc, 0, v21, vcc
	v_add_co_u32_e32 v34, vcc, s4, v20
	s_mov_b32 s4, 0x2e000
	s_nop 0
	v_addc_co_u32_e32 v35, vcc, 0, v21, vcc
	v_add_co_u32_e32 v36, vcc, s4, v20
	s_mov_b32 s4, 0x30000
	s_nop 0
	v_addc_co_u32_e32 v37, vcc, 0, v21, vcc
	global_load_dword v52, v[22:23], off nt
	global_load_dword v53, v[24:25], off nt
	global_load_dword v54, v[26:27], off nt
	global_load_dword v55, v[28:29], off nt
	global_load_dword v56, v[30:31], off nt
	global_load_dword v57, v[32:33], off nt
	global_load_dword v58, v[34:35], off nt
	s_nop 0
	global_load_dword v36, v[36:37], off nt
	v_add_co_u32_e32 v22, vcc, s4, v20
	s_mov_b32 s4, 0x32000
	s_nop 0
	v_addc_co_u32_e32 v23, vcc, 0, v21, vcc
	v_add_co_u32_e32 v24, vcc, s4, v20
	s_mov_b32 s4, 0x34000
	s_nop 0
	v_addc_co_u32_e32 v25, vcc, 0, v21, vcc
	v_add_co_u32_e32 v26, vcc, s4, v20
	s_mov_b32 s4, 0x36000
	s_nop 0
	v_addc_co_u32_e32 v27, vcc, 0, v21, vcc
	v_add_co_u32_e32 v28, vcc, s4, v20
	s_mov_b32 s4, 0x38000
	s_nop 0
	v_addc_co_u32_e32 v29, vcc, 0, v21, vcc
	v_add_co_u32_e32 v30, vcc, s4, v20
	s_mov_b32 s4, 0x3a000
	s_nop 0
	v_addc_co_u32_e32 v31, vcc, 0, v21, vcc
	v_add_co_u32_e32 v32, vcc, s4, v20
	s_mov_b32 s4, 0x3c000
	s_nop 0
	v_addc_co_u32_e32 v33, vcc, 0, v21, vcc
	v_add_co_u32_e32 v34, vcc, s4, v20
	s_mov_b32 s4, 0x3e000
	s_nop 0
	v_addc_co_u32_e32 v35, vcc, 0, v21, vcc
	v_add_co_u32_e32 v20, vcc, s4, v20
	s_movk_i32 s3, 0x7fff
	s_nop 0
	v_addc_co_u32_e32 v21, vcc, 0, v21, vcc
	global_load_dword v22, v[22:23], off nt
	s_nop 0
	global_load_dword v23, v[24:25], off nt
	s_nop 0
	global_load_dword v24, v[26:27], off nt
	global_load_dword v25, v[28:29], off nt
	s_nop 0
	global_load_dword v26, v[30:31], off nt
	global_load_dword v27, v[32:33], off nt
	global_load_dword v28, v[34:35], off nt
	s_nop 0
	global_load_dword v20, v[20:21], off nt
	s_waitcnt vmcnt(30)
	ds_write2_b32 v4, v3, v19 offset1:66
	s_waitcnt vmcnt(28)
	ds_write2_b32 v4, v38, v39 offset0:132 offset1:198
	s_waitcnt vmcnt(26)
	ds_write2_b32 v10, v40, v41 offset0:8 offset1:74
	s_waitcnt vmcnt(24)
	ds_write2_b32 v10, v42, v43 offset0:140 offset1:206
	s_waitcnt vmcnt(22)
	ds_write2_b32 v11, v44, v45 offset0:16 offset1:82
	s_waitcnt vmcnt(20)
	ds_write2_b32 v11, v46, v47 offset0:148 offset1:214
	s_waitcnt vmcnt(18)
	ds_write2_b32 v12, v48, v49 offset0:24 offset1:90
	s_waitcnt vmcnt(16)
	ds_write2_b32 v12, v50, v51 offset0:156 offset1:222
	s_waitcnt vmcnt(14)
	ds_write2_b32 v13, v52, v53 offset0:32 offset1:98
	s_waitcnt vmcnt(12)
	ds_write2_b32 v13, v54, v55 offset0:164 offset1:230
	s_waitcnt vmcnt(10)
	ds_write2_b32 v16, v56, v57 offset0:40 offset1:106
	s_waitcnt vmcnt(8)
	ds_write2_b32 v16, v58, v36 offset0:172 offset1:238
	s_waitcnt vmcnt(6)
	ds_write2_b32 v17, v22, v23 offset0:48 offset1:114
	s_waitcnt vmcnt(4)
	ds_write2_b32 v17, v24, v25 offset0:180 offset1:246
	s_waitcnt vmcnt(2)
	ds_write2_b32 v18, v26, v27 offset0:56 offset1:122
	s_waitcnt vmcnt(0)
	ds_write2_b32 v18, v28, v20 offset0:188 offset1:254
	s_waitcnt lgkmcnt(0)
	ds_read2_b32 v[24:25], v6 offset1:8
	ds_read2_b32 v[28:29], v6 offset0:33 offset1:41
	ds_read2_b32 v[30:31], v6 offset0:66 offset1:74
	v_mov_b32_e32 v3, v15
	ds_read2_b32 v[32:33], v6 offset0:99 offset1:107
	v_lshl_add_u64 v[20:21], s[14:15], 0, v[2:3]
	s_waitcnt lgkmcnt(3)
	v_bfe_u32 v3, v24, 16, 1
	v_add3_u32 v3, v24, v3, s3
	s_waitcnt lgkmcnt(2)
	v_bfe_u32 v19, v28, 16, 1
	ds_read2_b32 v[34:35], v6 offset0:132 offset1:140
	s_mov_b64 s[14:15], 0xb00000
	v_lshrrev_b32_e32 v3, 16, v3
	v_add3_u32 v19, v28, v19, s3
	ds_read2_b32 v[36:37], v6 offset0:165 offset1:173
	v_lshl_add_u64 v[26:27], v[20:21], 0, s[14:15]
	v_and_or_b32 v20, v19, s69, v3
	s_waitcnt lgkmcnt(3)
	v_bfe_u32 v3, v30, 16, 1
	v_add3_u32 v3, v30, v3, s3
	s_waitcnt lgkmcnt(2)
	v_bfe_u32 v19, v32, 16, 1
	ds_read2_b32 v[38:39], v6 offset0:198 offset1:206
	v_lshrrev_b32_e32 v3, 16, v3
	v_add3_u32 v19, v32, v19, s3
	ds_read2_b32 v[40:41], v6 offset0:231 offset1:239
	v_and_or_b32 v21, v19, s69, v3
	s_waitcnt lgkmcnt(3)
	v_bfe_u32 v3, v34, 16, 1
	v_add3_u32 v3, v34, v3, s3
	s_waitcnt lgkmcnt(2)
	v_bfe_u32 v19, v36, 16, 1
	v_lshrrev_b32_e32 v3, 16, v3
	v_add3_u32 v19, v36, v19, s3
	v_and_or_b32 v22, v19, s69, v3
	s_waitcnt lgkmcnt(1)
	v_bfe_u32 v3, v38, 16, 1
	v_add3_u32 v3, v38, v3, s3
	s_waitcnt lgkmcnt(0)
	v_bfe_u32 v19, v40, 16, 1
	v_lshrrev_b32_e32 v3, 16, v3
	v_add3_u32 v19, v40, v19, s3
	v_add_u32_e32 v42, s2, v5
	v_and_or_b32 v23, v19, s69, v3
	v_ashrrev_i32_e32 v43, 31, v42
	v_bfe_u32 v3, v25, 16, 1
	v_lshlrev_b64 v[42:43], 11, v[42:43]
	v_add3_u32 v3, v25, v3, s3
	v_bfe_u32 v19, v29, 16, 1
	v_lshl_add_u64 v[42:43], v[26:27], 0, v[42:43]
	v_lshrrev_b32_e32 v3, 16, v3
	v_add3_u32 v19, v29, v19, s3
	global_store_dwordx4 v[42:43], v[20:23], off
	v_add_u32_e32 v24, s2, v7
	v_ashrrev_i32_e32 v25, 31, v24
	v_and_or_b32 v20, v19, s69, v3
	v_bfe_u32 v3, v31, 16, 1
	v_add3_u32 v3, v31, v3, s3
	v_bfe_u32 v19, v33, 16, 1
	v_lshrrev_b32_e32 v3, 16, v3
	v_add3_u32 v19, v33, v19, s3
	v_and_or_b32 v21, v19, s69, v3
	v_bfe_u32 v3, v35, 16, 1
	v_add3_u32 v3, v35, v3, s3
	v_bfe_u32 v19, v37, 16, 1
	v_lshrrev_b32_e32 v3, 16, v3
	v_add3_u32 v19, v37, v19, s3
	v_and_or_b32 v22, v19, s69, v3
	v_bfe_u32 v3, v39, 16, 1
	v_add3_u32 v3, v39, v3, s3
	v_bfe_u32 v19, v41, 16, 1
	v_lshrrev_b32_e32 v3, 16, v3
	v_add3_u32 v19, v41, v19, s3
	v_lshlrev_b64 v[24:25], 11, v[24:25]
	v_and_or_b32 v23, v19, s69, v3
	ds_read2_b32 v[28:29], v6 offset0:16 offset1:24
	v_lshl_add_u64 v[24:25], v[26:27], 0, v[24:25]
	global_store_dwordx4 v[24:25], v[20:23], off
	ds_read2_b32 v[24:25], v6 offset0:49 offset1:57
	ds_read2_b32 v[30:31], v6 offset0:82 offset1:90
	ds_read2_b32 v[32:33], v6 offset0:115 offset1:123
	s_waitcnt lgkmcnt(3)
	v_bfe_u32 v3, v28, 16, 1
	v_add3_u32 v3, v28, v3, s3
	s_waitcnt lgkmcnt(2)
	v_bfe_u32 v19, v24, 16, 1
	ds_read2_b32 v[34:35], v6 offset0:148 offset1:156
	v_lshrrev_b32_e32 v3, 16, v3
	v_add3_u32 v19, v24, v19, s3
	ds_read2_b32 v[36:37], v6 offset0:181 offset1:189
	v_and_or_b32 v20, v19, s69, v3
	s_waitcnt lgkmcnt(3)
	v_bfe_u32 v3, v30, 16, 1
	v_add3_u32 v3, v30, v3, s3
	s_waitcnt lgkmcnt(2)
	v_bfe_u32 v19, v32, 16, 1
	ds_read2_b32 v[38:39], v6 offset0:214 offset1:222
	v_lshrrev_b32_e32 v3, 16, v3
	v_add3_u32 v19, v32, v19, s3
	ds_read2_b32 v[40:41], v6 offset0:247 offset1:255
	v_and_or_b32 v21, v19, s69, v3
	s_waitcnt lgkmcnt(3)
	v_bfe_u32 v3, v34, 16, 1
	v_add3_u32 v3, v34, v3, s3
	s_waitcnt lgkmcnt(2)
	v_bfe_u32 v19, v36, 16, 1
	v_lshrrev_b32_e32 v3, 16, v3
	v_add3_u32 v19, v36, v19, s3
	v_and_or_b32 v22, v19, s69, v3
	s_waitcnt lgkmcnt(1)
	v_bfe_u32 v3, v38, 16, 1
	v_add3_u32 v3, v38, v3, s3
	s_waitcnt lgkmcnt(0)
	v_bfe_u32 v19, v40, 16, 1
	v_lshrrev_b32_e32 v3, 16, v3
	v_add3_u32 v19, v40, v19, s3
	v_add_u32_e32 v42, s2, v8
	v_and_or_b32 v23, v19, s69, v3
	v_ashrrev_i32_e32 v43, 31, v42
	v_bfe_u32 v3, v29, 16, 1
	v_lshlrev_b64 v[42:43], 11, v[42:43]
	v_add3_u32 v3, v29, v3, s3
	v_bfe_u32 v19, v25, 16, 1
	v_lshl_add_u64 v[42:43], v[26:27], 0, v[42:43]
	v_lshrrev_b32_e32 v3, 16, v3
	v_add3_u32 v19, v25, v19, s3
	global_store_dwordx4 v[42:43], v[20:23], off
	v_add_u32_e32 v24, s2, v9
	v_ashrrev_i32_e32 v25, 31, v24
	v_and_or_b32 v20, v19, s69, v3
	v_bfe_u32 v3, v31, 16, 1
	v_add3_u32 v3, v31, v3, s3
	v_bfe_u32 v19, v33, 16, 1
	v_lshrrev_b32_e32 v3, 16, v3
	v_add3_u32 v19, v33, v19, s3
	v_and_or_b32 v21, v19, s69, v3
	v_bfe_u32 v3, v35, 16, 1
	v_add3_u32 v3, v35, v3, s3
	v_bfe_u32 v19, v37, 16, 1
	v_lshrrev_b32_e32 v3, 16, v3
	v_add3_u32 v19, v37, v19, s3
	v_and_or_b32 v22, v19, s69, v3
	v_bfe_u32 v3, v39, 16, 1
	v_add3_u32 v3, v39, v3, s3
	v_bfe_u32 v19, v41, 16, 1
	v_lshrrev_b32_e32 v3, 16, v3
	v_add3_u32 v19, v41, v19, s3
	v_lshlrev_b64 v[24:25], 11, v[24:25]
	v_and_or_b32 v23, v19, s69, v3
	v_lshl_add_u64 v[24:25], v[26:27], 0, v[24:25]
	global_store_dwordx4 v[24:25], v[20:23], off
	s_waitcnt lgkmcnt(0)
	v_readlane_b32 s41, v254, 32
	v_readlane_b32 s44, v254, 35
	v_readlane_b32 s45, v254, 36
	v_readlane_b32 s46, v254, 37
	v_readlane_b32 s47, v254, 38

.LBB0_225:
	s_andn2_b64 vcc, exec, s[2:3]
	s_cbranch_vccnz .LBB0_227
	s_mul_i32 s2, s0, 0xffffc500
	s_add_i32 s2, s10, s2
	s_addk_i32 s2, 0xfe00
	s_and_b32 s3, s2, 0x7fffffc0
	s_and_b32 s2, s5, 0x3e0
	s_lshl_b64 s[14:15], s[0:1], 21
	v_readlane_b32 s40, v254, 31
	v_readlane_b32 s41, v254, 32
	s_add_u32 s4, s40, s14
	s_addc_u32 s9, s41, s15
	s_lshl_b32 s14, s2, 2
	v_add_u32_e32 v20, s3, v1
	s_add_u32 s14, s4, s14
	s_addc_u32 s15, s9, 0
	v_ashrrev_i32_e32 v21, 31, v20
	v_lshl_add_u64 v[22:23], s[14:15], 0, v[14:15]
	v_lshlrev_b64 v[20:21], 12, v[20:21]
	v_lshl_add_u64 v[20:21], v[22:23], 0, v[20:21]
	s_movk_i32 s4, 0x2000
	v_add_co_u32_e32 v22, vcc, s4, v20
	s_movk_i32 s4, 0x4000
	s_nop 0
	v_addc_co_u32_e32 v23, vcc, 0, v21, vcc
	v_add_co_u32_e32 v24, vcc, s4, v20
	s_movk_i32 s4, 0x6000
	s_nop 0
	v_addc_co_u32_e32 v25, vcc, 0, v21, vcc
	v_add_co_u32_e32 v26, vcc, s4, v20
	s_mov_b32 s4, 0xa000
	s_nop 0
	v_addc_co_u32_e32 v27, vcc, 0, v21, vcc
	v_add_co_u32_e32 v28, vcc, s66, v20
	s_lshl_b32 s3, s3, 1
	s_nop 0
	v_addc_co_u32_e32 v29, vcc, 0, v21, vcc
	v_add_co_u32_e32 v30, vcc, s4, v20
	s_mov_b32 s4, 0xc000
	s_nop 0
	v_addc_co_u32_e32 v31, vcc, 0, v21, vcc
	v_add_co_u32_e32 v32, vcc, s4, v20
	s_mov_b32 s4, 0xe000
	s_nop 0
	v_addc_co_u32_e32 v33, vcc, 0, v21, vcc
	v_add_co_u32_e32 v34, vcc, s4, v20
	s_mov_b32 s4, 0x12000
	s_nop 0
	v_addc_co_u32_e32 v35, vcc, 0, v21, vcc
	global_load_dword v3, v[20:21], off nt
	global_load_dword v19, v[22:23], off nt
	global_load_dword v38, v[24:25], off nt
	global_load_dword v39, v[26:27], off nt
	global_load_dword v40, v[28:29], off nt
	global_load_dword v41, v[30:31], off nt
	global_load_dword v42, v[32:33], off nt
	global_load_dword v43, v[34:35], off nt
	v_add_co_u32_e32 v22, vcc, s67, v20
	s_add_u32 s14, s13, s3
	s_nop 0
	v_addc_co_u32_e32 v23, vcc, 0, v21, vcc
	v_add_co_u32_e32 v24, vcc, s4, v20
	s_mov_b32 s4, 0x14000
	s_nop 0
	v_addc_co_u32_e32 v25, vcc, 0, v21, vcc
	v_add_co_u32_e32 v26, vcc, s4, v20
	s_mov_b32 s4, 0x16000
	s_nop 0
	v_addc_co_u32_e32 v27, vcc, 0, v21, vcc
	v_add_co_u32_e32 v28, vcc, s4, v20
	s_mov_b32 s4, 0x1a000
	s_nop 0
	v_addc_co_u32_e32 v29, vcc, 0, v21, vcc
	v_add_co_u32_e32 v30, vcc, s68, v20
	s_addc_u32 s15, s12, 0
	s_nop 0
	v_addc_co_u32_e32 v31, vcc, 0, v21, vcc
	v_add_co_u32_e32 v32, vcc, s4, v20
	s_mov_b32 s4, 0x1c000
	s_nop 0
	v_addc_co_u32_e32 v33, vcc, 0, v21, vcc
	v_add_co_u32_e32 v34, vcc, s4, v20
	s_mov_b32 s4, 0x1e000
	s_nop 0
	v_addc_co_u32_e32 v35, vcc, 0, v21, vcc
	v_add_co_u32_e32 v36, vcc, s4, v20
	s_mov_b32 s4, 0x20000
	s_nop 0
	v_addc_co_u32_e32 v37, vcc, 0, v21, vcc
	global_load_dword v44, v[22:23], off nt
	global_load_dword v45, v[24:25], off nt
	global_load_dword v46, v[26:27], off nt
	global_load_dword v47, v[28:29], off nt
	global_load_dword v48, v[30:31], off nt
	global_load_dword v49, v[32:33], off nt
	global_load_dword v50, v[34:35], off nt
	global_load_dword v51, v[36:37], off nt
	v_add_co_u32_e32 v22, vcc, s4, v20
	s_mov_b32 s4, 0x22000
	s_nop 0
	v_addc_co_u32_e32 v23, vcc, 0, v21, vcc
	v_add_co_u32_e32 v24, vcc, s4, v20
	s_mov_b32 s4, 0x24000
	s_nop 0
	v_addc_co_u32_e32 v25, vcc, 0, v21, vcc
	v_add_co_u32_e32 v26, vcc, s4, v20
	s_mov_b32 s4, 0x26000
	s_nop 0
	v_addc_co_u32_e32 v27, vcc, 0, v21, vcc
	v_add_co_u32_e32 v28, vcc, s4, v20
	s_mov_b32 s4, 0x28000
	s_nop 0
	v_addc_co_u32_e32 v29, vcc, 0, v21, vcc
	v_add_co_u32_e32 v30, vcc, s4, v20
	s_mov_b32 s4, 0x2a000
	s_nop 0
	v_addc_co_u32_e32 v31, vcc, 0, v21, vcc
	v_add_co_u32_e32 v32, vcc, s4, v20
	s_mov_b32 s4, 0x2c000
	s_nop 0
	v_addc_co_u32_e32 v33, vcc, 0, v21, vcc
	v_add_co_u32_e32 v34, vcc, s4, v20
	s_mov_b32 s4, 0x2e000
	s_nop 0
	v_addc_co_u32_e32 v35, vcc, 0, v21, vcc
	v_add_co_u32_e32 v36, vcc, s4, v20
	s_mov_b32 s4, 0x30000
	s_nop 0
	v_addc_co_u32_e32 v37, vcc, 0, v21, vcc
	global_load_dword v52, v[22:23], off nt
	global_load_dword v53, v[24:25], off nt
	global_load_dword v54, v[26:27], off nt
	global_load_dword v55, v[28:29], off nt
	global_load_dword v56, v[30:31], off nt
	global_load_dword v57, v[32:33], off nt
	global_load_dword v58, v[34:35], off nt
	s_nop 0
	global_load_dword v36, v[36:37], off nt
	v_add_co_u32_e32 v22, vcc, s4, v20
	s_mov_b32 s4, 0x32000
	s_nop 0
	v_addc_co_u32_e32 v23, vcc, 0, v21, vcc
	v_add_co_u32_e32 v24, vcc, s4, v20
	s_mov_b32 s4, 0x34000
	s_nop 0
	v_addc_co_u32_e32 v25, vcc, 0, v21, vcc
	v_add_co_u32_e32 v26, vcc, s4, v20
	s_mov_b32 s4, 0x36000
	s_nop 0
	v_addc_co_u32_e32 v27, vcc, 0, v21, vcc
	v_add_co_u32_e32 v28, vcc, s4, v20
	s_mov_b32 s4, 0x38000
	s_nop 0
	v_addc_co_u32_e32 v29, vcc, 0, v21, vcc
	v_add_co_u32_e32 v30, vcc, s4, v20
	s_mov_b32 s4, 0x3a000
	s_nop 0
	v_addc_co_u32_e32 v31, vcc, 0, v21, vcc
	v_add_co_u32_e32 v32, vcc, s4, v20
	s_mov_b32 s4, 0x3c000
	s_nop 0
	v_addc_co_u32_e32 v33, vcc, 0, v21, vcc
	v_add_co_u32_e32 v34, vcc, s4, v20
	s_mov_b32 s4, 0x3e000
	s_nop 0
	v_addc_co_u32_e32 v35, vcc, 0, v21, vcc
	v_add_co_u32_e32 v20, vcc, s4, v20
	s_movk_i32 s3, 0x7fff
	s_nop 0
	v_addc_co_u32_e32 v21, vcc, 0, v21, vcc
	global_load_dword v22, v[22:23], off nt
	s_nop 0
	global_load_dword v23, v[24:25], off nt
	s_nop 0
	global_load_dword v24, v[26:27], off nt
	global_load_dword v25, v[28:29], off nt
	s_nop 0
	global_load_dword v26, v[30:31], off nt
	global_load_dword v27, v[32:33], off nt
	global_load_dword v28, v[34:35], off nt
	s_nop 0
	global_load_dword v20, v[20:21], off nt
	s_waitcnt vmcnt(30)
	ds_write2_b32 v4, v3, v19 offset1:66
	s_waitcnt vmcnt(28)
	ds_write2_b32 v4, v38, v39 offset0:132 offset1:198
	s_waitcnt vmcnt(26)
	ds_write2_b32 v10, v40, v41 offset0:8 offset1:74
	s_waitcnt vmcnt(24)
	ds_write2_b32 v10, v42, v43 offset0:140 offset1:206
	s_waitcnt vmcnt(22)
	ds_write2_b32 v11, v44, v45 offset0:16 offset1:82
	s_waitcnt vmcnt(20)
	ds_write2_b32 v11, v46, v47 offset0:148 offset1:214
	s_waitcnt vmcnt(18)
	ds_write2_b32 v12, v48, v49 offset0:24 offset1:90
	s_waitcnt vmcnt(16)
	ds_write2_b32 v12, v50, v51 offset0:156 offset1:222
	s_waitcnt vmcnt(14)
	ds_write2_b32 v13, v52, v53 offset0:32 offset1:98
	s_waitcnt vmcnt(12)
	ds_write2_b32 v13, v54, v55 offset0:164 offset1:230
	s_waitcnt vmcnt(10)
	ds_write2_b32 v16, v56, v57 offset0:40 offset1:106
	s_waitcnt vmcnt(8)
	ds_write2_b32 v16, v58, v36 offset0:172 offset1:238
	s_waitcnt vmcnt(6)
	ds_write2_b32 v17, v22, v23 offset0:48 offset1:114
	s_waitcnt vmcnt(4)
	ds_write2_b32 v17, v24, v25 offset0:180 offset1:246
	s_waitcnt vmcnt(2)
	ds_write2_b32 v18, v26, v27 offset0:56 offset1:122
	s_waitcnt vmcnt(0)
	ds_write2_b32 v18, v28, v20 offset0:188 offset1:254
	s_waitcnt lgkmcnt(0)
	ds_read2_b32 v[24:25], v6 offset1:8
	ds_read2_b32 v[28:29], v6 offset0:33 offset1:41
	ds_read2_b32 v[30:31], v6 offset0:66 offset1:74
	v_mov_b32_e32 v3, v15
	ds_read2_b32 v[32:33], v6 offset0:99 offset1:107
	v_lshl_add_u64 v[20:21], s[14:15], 0, v[2:3]
	s_waitcnt lgkmcnt(3)
	v_bfe_u32 v3, v24, 16, 1
	v_add3_u32 v3, v24, v3, s3
	s_waitcnt lgkmcnt(2)
	v_bfe_u32 v19, v28, 16, 1
	ds_read2_b32 v[34:35], v6 offset0:132 offset1:140
	s_mov_b64 s[14:15], 0x900400
	v_lshrrev_b32_e32 v3, 16, v3
	v_add3_u32 v19, v28, v19, s3
	ds_read2_b32 v[36:37], v6 offset0:165 offset1:173
	v_lshl_add_u64 v[26:27], v[20:21], 0, s[14:15]
	v_and_or_b32 v20, v19, s69, v3
	s_waitcnt lgkmcnt(3)
	v_bfe_u32 v3, v30, 16, 1
	v_add3_u32 v3, v30, v3, s3
	s_waitcnt lgkmcnt(2)
	v_bfe_u32 v19, v32, 16, 1
	ds_read2_b32 v[38:39], v6 offset0:198 offset1:206
	v_lshrrev_b32_e32 v3, 16, v3
	v_add3_u32 v19, v32, v19, s3
	ds_read2_b32 v[40:41], v6 offset0:231 offset1:239
	v_and_or_b32 v21, v19, s69, v3
	s_waitcnt lgkmcnt(3)
	v_bfe_u32 v3, v34, 16, 1
	v_add3_u32 v3, v34, v3, s3
	s_waitcnt lgkmcnt(2)
	v_bfe_u32 v19, v36, 16, 1
	v_lshrrev_b32_e32 v3, 16, v3
	v_add3_u32 v19, v36, v19, s3
	v_and_or_b32 v22, v19, s69, v3
	s_waitcnt lgkmcnt(1)
	v_bfe_u32 v3, v38, 16, 1
	v_add3_u32 v3, v38, v3, s3
	s_waitcnt lgkmcnt(0)
	v_bfe_u32 v19, v40, 16, 1
	v_lshrrev_b32_e32 v3, 16, v3
	v_add3_u32 v19, v40, v19, s3
	v_add_u32_e32 v42, s2, v5
	v_and_or_b32 v23, v19, s69, v3
	v_ashrrev_i32_e32 v43, 31, v42
	v_bfe_u32 v3, v25, 16, 1
	v_lshlrev_b64 v[42:43], 11, v[42:43]
	v_add3_u32 v3, v25, v3, s3
	v_bfe_u32 v19, v29, 16, 1
	v_lshl_add_u64 v[42:43], v[26:27], 0, v[42:43]
	v_lshrrev_b32_e32 v3, 16, v3
	v_add3_u32 v19, v29, v19, s3
	global_store_dwordx4 v[42:43], v[20:23], off
	v_add_u32_e32 v24, s2, v7
	v_ashrrev_i32_e32 v25, 31, v24
	v_and_or_b32 v20, v19, s69, v3
	v_bfe_u32 v3, v31, 16, 1
	v_add3_u32 v3, v31, v3, s3
	v_bfe_u32 v19, v33, 16, 1
	v_lshrrev_b32_e32 v3, 16, v3
	v_add3_u32 v19, v33, v19, s3
	v_and_or_b32 v21, v19, s69, v3
	v_bfe_u32 v3, v35, 16, 1
	v_add3_u32 v3, v35, v3, s3
	v_bfe_u32 v19, v37, 16, 1
	v_lshrrev_b32_e32 v3, 16, v3
	v_add3_u32 v19, v37, v19, s3
	v_and_or_b32 v22, v19, s69, v3
	v_bfe_u32 v3, v39, 16, 1
	v_add3_u32 v3, v39, v3, s3
	v_bfe_u32 v19, v41, 16, 1
	v_lshrrev_b32_e32 v3, 16, v3
	v_add3_u32 v19, v41, v19, s3
	v_lshlrev_b64 v[24:25], 11, v[24:25]
	v_and_or_b32 v23, v19, s69, v3
	ds_read2_b32 v[28:29], v6 offset0:16 offset1:24
	v_lshl_add_u64 v[24:25], v[26:27], 0, v[24:25]
	global_store_dwordx4 v[24:25], v[20:23], off
	ds_read2_b32 v[24:25], v6 offset0:49 offset1:57
	ds_read2_b32 v[30:31], v6 offset0:82 offset1:90
	ds_read2_b32 v[32:33], v6 offset0:115 offset1:123
	s_waitcnt lgkmcnt(3)
	v_bfe_u32 v3, v28, 16, 1
	v_add3_u32 v3, v28, v3, s3
	s_waitcnt lgkmcnt(2)
	v_bfe_u32 v19, v24, 16, 1
	ds_read2_b32 v[34:35], v6 offset0:148 offset1:156
	v_lshrrev_b32_e32 v3, 16, v3
	v_add3_u32 v19, v24, v19, s3
	ds_read2_b32 v[36:37], v6 offset0:181 offset1:189
	v_and_or_b32 v20, v19, s69, v3
	s_waitcnt lgkmcnt(3)
	v_bfe_u32 v3, v30, 16, 1
	v_add3_u32 v3, v30, v3, s3
	s_waitcnt lgkmcnt(2)
	v_bfe_u32 v19, v32, 16, 1
	ds_read2_b32 v[38:39], v6 offset0:214 offset1:222
	v_lshrrev_b32_e32 v3, 16, v3
	v_add3_u32 v19, v32, v19, s3
	ds_read2_b32 v[40:41], v6 offset0:247 offset1:255
	v_and_or_b32 v21, v19, s69, v3
	s_waitcnt lgkmcnt(3)
	v_bfe_u32 v3, v34, 16, 1
	v_add3_u32 v3, v34, v3, s3
	s_waitcnt lgkmcnt(2)
	v_bfe_u32 v19, v36, 16, 1
	v_lshrrev_b32_e32 v3, 16, v3
	v_add3_u32 v19, v36, v19, s3
	v_and_or_b32 v22, v19, s69, v3
	s_waitcnt lgkmcnt(1)
	v_bfe_u32 v3, v38, 16, 1
	v_add3_u32 v3, v38, v3, s3
	s_waitcnt lgkmcnt(0)
	v_bfe_u32 v19, v40, 16, 1
	v_lshrrev_b32_e32 v3, 16, v3
	v_add3_u32 v19, v40, v19, s3
	v_add_u32_e32 v42, s2, v8
	v_and_or_b32 v23, v19, s69, v3
	v_ashrrev_i32_e32 v43, 31, v42
	v_bfe_u32 v3, v29, 16, 1
	v_lshlrev_b64 v[42:43], 11, v[42:43]
	v_add3_u32 v3, v29, v3, s3
	v_bfe_u32 v19, v25, 16, 1
	v_lshl_add_u64 v[42:43], v[26:27], 0, v[42:43]
	v_lshrrev_b32_e32 v3, 16, v3
	v_add3_u32 v19, v25, v19, s3
	global_store_dwordx4 v[42:43], v[20:23], off
	v_add_u32_e32 v24, s2, v9
	v_ashrrev_i32_e32 v25, 31, v24
	v_and_or_b32 v20, v19, s69, v3
	v_bfe_u32 v3, v31, 16, 1
	v_add3_u32 v3, v31, v3, s3
	v_bfe_u32 v19, v33, 16, 1
	v_lshrrev_b32_e32 v3, 16, v3
	v_add3_u32 v19, v33, v19, s3
	v_and_or_b32 v21, v19, s69, v3
	v_bfe_u32 v3, v35, 16, 1
	v_add3_u32 v3, v35, v3, s3
	v_bfe_u32 v19, v37, 16, 1
	v_lshrrev_b32_e32 v3, 16, v3
	v_add3_u32 v19, v37, v19, s3
	v_and_or_b32 v22, v19, s69, v3
	v_bfe_u32 v3, v39, 16, 1
	v_add3_u32 v3, v39, v3, s3
	v_bfe_u32 v19, v41, 16, 1
	v_lshrrev_b32_e32 v3, 16, v3
	v_add3_u32 v19, v41, v19, s3
	v_lshlrev_b64 v[24:25], 11, v[24:25]
	v_and_or_b32 v23, v19, s69, v3
	v_lshl_add_u64 v[24:25], v[26:27], 0, v[24:25]
	global_store_dwordx4 v[24:25], v[20:23], off
	s_waitcnt lgkmcnt(0)
	v_readlane_b32 s42, v254, 33
	v_readlane_b32 s43, v254, 34
	v_readlane_b32 s44, v254, 35
	v_readlane_b32 s45, v254, 36
	v_readlane_b32 s46, v254, 37
	v_readlane_b32 s47, v254, 38

.LBB0_228:
	s_andn2_b64 vcc, exec, s[2:3]
	s_cbranch_vccnz .LBB0_230
	s_mul_i32 s2, s0, 0xffffc500
	s_add_i32 s2, s10, s2
	v_readlane_b32 s40, v250, 15
	s_and_b32 s3, s2, 0x7fffffc0
	s_and_b32 s2, s5, 0x3e0
	s_lshl_b64 s[14:15], s[0:1], 21
	v_readlane_b32 s54, v250, 29
	v_readlane_b32 s55, v250, 30
	s_add_u32 s1, s54, s14
	s_addc_u32 s4, s55, s15
	s_lshl_b32 s9, s2, 2
	v_add_u32_e32 v20, s3, v1
	s_add_u32 s14, s1, s9
	s_addc_u32 s15, s4, 0
	v_ashrrev_i32_e32 v21, 31, v20
	v_lshl_add_u64 v[22:23], s[14:15], 0, v[14:15]
	v_lshlrev_b64 v[20:21], 12, v[20:21]
	v_lshl_add_u64 v[20:21], v[22:23], 0, v[20:21]
	s_movk_i32 s1, 0x2000
	v_add_co_u32_e32 v22, vcc, s1, v20
	s_movk_i32 s1, 0x4000
	s_nop 0
	v_addc_co_u32_e32 v23, vcc, 0, v21, vcc
	v_add_co_u32_e32 v24, vcc, s1, v20
	s_movk_i32 s1, 0x6000
	s_nop 0
	v_addc_co_u32_e32 v25, vcc, 0, v21, vcc
	v_add_co_u32_e32 v26, vcc, s1, v20
	s_mov_b32 s1, 0xa000
	s_nop 0
	v_addc_co_u32_e32 v27, vcc, 0, v21, vcc
	v_add_co_u32_e32 v28, vcc, s66, v20
	v_readlane_b32 s21, v250, 10
	s_nop 0
	v_addc_co_u32_e32 v29, vcc, 0, v21, vcc
	v_add_co_u32_e32 v30, vcc, s1, v20
	s_mov_b32 s1, 0xc000
	s_nop 0
	v_addc_co_u32_e32 v31, vcc, 0, v21, vcc
	v_add_co_u32_e32 v32, vcc, s1, v20
	s_mov_b32 s1, 0xe000
	s_nop 0
	v_addc_co_u32_e32 v33, vcc, 0, v21, vcc
	v_add_co_u32_e32 v34, vcc, s1, v20
	s_mov_b32 s1, 0x12000
	s_nop 0
	v_addc_co_u32_e32 v35, vcc, 0, v21, vcc
	global_load_dword v3, v[20:21], off nt
	global_load_dword v19, v[22:23], off nt
	global_load_dword v38, v[24:25], off nt
	global_load_dword v39, v[26:27], off nt
	global_load_dword v40, v[28:29], off nt
	global_load_dword v41, v[30:31], off nt
	global_load_dword v42, v[32:33], off nt
	global_load_dword v43, v[34:35], off nt
	v_add_co_u32_e32 v22, vcc, s67, v20
	v_readlane_b32 s41, v250, 16
	s_nop 0
	v_addc_co_u32_e32 v23, vcc, 0, v21, vcc
	v_add_co_u32_e32 v24, vcc, s1, v20
	s_mov_b32 s1, 0x14000
	s_nop 0
	v_addc_co_u32_e32 v25, vcc, 0, v21, vcc
	v_add_co_u32_e32 v26, vcc, s1, v20
	s_mov_b32 s1, 0x16000
	s_nop 0
	v_addc_co_u32_e32 v27, vcc, 0, v21, vcc
	v_add_co_u32_e32 v28, vcc, s1, v20
	s_mov_b32 s1, 0x1a000
	s_nop 0
	v_addc_co_u32_e32 v29, vcc, 0, v21, vcc
	v_add_co_u32_e32 v30, vcc, s68, v20
	v_readlane_b32 s42, v250, 17
	s_nop 0
	v_addc_co_u32_e32 v31, vcc, 0, v21, vcc
	v_add_co_u32_e32 v32, vcc, s1, v20
	s_mov_b32 s1, 0x1c000
	s_nop 0
	v_addc_co_u32_e32 v33, vcc, 0, v21, vcc
	v_add_co_u32_e32 v34, vcc, s1, v20
	s_mov_b32 s1, 0x1e000
	s_nop 0
	v_addc_co_u32_e32 v35, vcc, 0, v21, vcc
	v_add_co_u32_e32 v36, vcc, s1, v20
	s_mov_b32 s1, 0x20000
	s_nop 0
	v_addc_co_u32_e32 v37, vcc, 0, v21, vcc
	global_load_dword v44, v[22:23], off nt
	global_load_dword v45, v[24:25], off nt
	global_load_dword v46, v[26:27], off nt
	global_load_dword v47, v[28:29], off nt
	global_load_dword v48, v[30:31], off nt
	global_load_dword v49, v[32:33], off nt
	global_load_dword v50, v[34:35], off nt
	global_load_dword v51, v[36:37], off nt
	v_add_co_u32_e32 v22, vcc, s1, v20
	s_mov_b32 s1, 0x22000
	s_nop 0
	v_addc_co_u32_e32 v23, vcc, 0, v21, vcc
	v_add_co_u32_e32 v24, vcc, s1, v20
	s_mov_b32 s1, 0x24000
	s_nop 0
	v_addc_co_u32_e32 v25, vcc, 0, v21, vcc
	v_add_co_u32_e32 v26, vcc, s1, v20
	s_mov_b32 s1, 0x26000
	s_nop 0
	v_addc_co_u32_e32 v27, vcc, 0, v21, vcc
	v_add_co_u32_e32 v28, vcc, s1, v20
	s_mov_b32 s1, 0x28000
	s_nop 0
	v_addc_co_u32_e32 v29, vcc, 0, v21, vcc
	v_add_co_u32_e32 v30, vcc, s1, v20
	s_mov_b32 s1, 0x2a000
	s_nop 0
	v_addc_co_u32_e32 v31, vcc, 0, v21, vcc
	v_add_co_u32_e32 v32, vcc, s1, v20
	s_mov_b32 s1, 0x2c000
	s_nop 0
	v_addc_co_u32_e32 v33, vcc, 0, v21, vcc
	v_add_co_u32_e32 v34, vcc, s1, v20
	s_mov_b32 s1, 0x2e000
	s_nop 0
	v_addc_co_u32_e32 v35, vcc, 0, v21, vcc
	v_add_co_u32_e32 v36, vcc, s1, v20
	s_mov_b32 s1, 0x30000
	s_nop 0
	v_addc_co_u32_e32 v37, vcc, 0, v21, vcc
	global_load_dword v52, v[22:23], off nt
	global_load_dword v53, v[24:25], off nt
	global_load_dword v54, v[26:27], off nt
	global_load_dword v55, v[28:29], off nt
	global_load_dword v56, v[30:31], off nt
	global_load_dword v57, v[32:33], off nt
	global_load_dword v58, v[34:35], off nt
	s_nop 0
	global_load_dword v36, v[36:37], off nt
	v_add_co_u32_e32 v22, vcc, s1, v20
	s_mov_b32 s1, 0x32000
	s_nop 0
	v_addc_co_u32_e32 v23, vcc, 0, v21, vcc
	v_add_co_u32_e32 v24, vcc, s1, v20
	s_mov_b32 s1, 0x34000
	s_nop 0
	v_addc_co_u32_e32 v25, vcc, 0, v21, vcc
	v_add_co_u32_e32 v26, vcc, s1, v20
	s_mov_b32 s1, 0x36000
	s_nop 0
	v_addc_co_u32_e32 v27, vcc, 0, v21, vcc
	v_add_co_u32_e32 v28, vcc, s1, v20
	s_mov_b32 s1, 0x38000
	s_nop 0
	v_addc_co_u32_e32 v29, vcc, 0, v21, vcc
	v_add_co_u32_e32 v30, vcc, s1, v20
	s_mov_b32 s1, 0x3a000
	s_nop 0
	v_addc_co_u32_e32 v31, vcc, 0, v21, vcc
	v_add_co_u32_e32 v32, vcc, s1, v20
	s_mov_b32 s1, 0x3c000
	s_nop 0
	v_addc_co_u32_e32 v33, vcc, 0, v21, vcc
	v_add_co_u32_e32 v34, vcc, s1, v20
	s_mov_b32 s1, 0x3e000
	s_nop 0
	v_addc_co_u32_e32 v35, vcc, 0, v21, vcc
	v_add_co_u32_e32 v20, vcc, s1, v20
	s_lshl_b32 s1, s3, 1
	s_nop 0
	v_addc_co_u32_e32 v21, vcc, 0, v21, vcc
	global_load_dword v22, v[22:23], off nt
	s_nop 0
	global_load_dword v23, v[24:25], off nt
	s_nop 0
	global_load_dword v24, v[26:27], off nt
	global_load_dword v25, v[28:29], off nt
	s_nop 0
	global_load_dword v26, v[30:31], off nt
	global_load_dword v27, v[32:33], off nt
	global_load_dword v28, v[34:35], off nt
	s_nop 0
	global_load_dword v20, v[20:21], off nt
	s_waitcnt vmcnt(30)
	ds_write2_b32 v4, v3, v19 offset1:66
	s_waitcnt vmcnt(28)
	ds_write2_b32 v4, v38, v39 offset0:132 offset1:198
	s_waitcnt vmcnt(26)
	ds_write2_b32 v10, v40, v41 offset0:8 offset1:74
	s_waitcnt vmcnt(24)
	ds_write2_b32 v10, v42, v43 offset0:140 offset1:206
	s_waitcnt vmcnt(22)
	ds_write2_b32 v11, v44, v45 offset0:16 offset1:82
	s_waitcnt vmcnt(20)
	ds_write2_b32 v11, v46, v47 offset0:148 offset1:214
	s_waitcnt vmcnt(18)
	ds_write2_b32 v12, v48, v49 offset0:24 offset1:90
	s_waitcnt vmcnt(16)
	ds_write2_b32 v12, v50, v51 offset0:156 offset1:222
	s_waitcnt vmcnt(14)
	ds_write2_b32 v13, v52, v53 offset0:32 offset1:98
	s_waitcnt vmcnt(12)
	ds_write2_b32 v13, v54, v55 offset0:164 offset1:230
	s_waitcnt vmcnt(10)
	ds_write2_b32 v16, v56, v57 offset0:40 offset1:106
	s_waitcnt vmcnt(8)
	ds_write2_b32 v16, v58, v36 offset0:172 offset1:238
	s_waitcnt vmcnt(6)
	ds_write2_b32 v17, v22, v23 offset0:48 offset1:114
	s_waitcnt vmcnt(4)
	ds_write2_b32 v17, v24, v25 offset0:180 offset1:246
	s_waitcnt vmcnt(2)
	ds_write2_b32 v18, v26, v27 offset0:56 offset1:122
	s_waitcnt vmcnt(0)
	ds_write2_b32 v18, v28, v20 offset0:188 offset1:254
	s_waitcnt lgkmcnt(0)
	ds_read2_b32 v[24:25], v6 offset1:8
	ds_read2_b32 v[28:29], v6 offset0:33 offset1:41
	s_add_u32 s14, s13, s1
	ds_read2_b32 v[30:31], v6 offset0:66 offset1:74
	s_addc_u32 s15, s12, 0
	v_mov_b32_e32 v3, v15
	ds_read2_b32 v[32:33], v6 offset0:99 offset1:107
	v_lshl_add_u64 v[20:21], s[14:15], 0, v[2:3]
	s_waitcnt lgkmcnt(3)
	v_bfe_u32 v3, v24, 16, 1
	s_movk_i32 s1, 0x7fff
	v_add3_u32 v3, v24, v3, s1
	s_waitcnt lgkmcnt(2)
	v_bfe_u32 v19, v28, 16, 1
	ds_read2_b32 v[34:35], v6 offset0:132 offset1:140
	s_mov_b64 s[14:15], 0x900000
	v_lshrrev_b32_e32 v3, 16, v3
	v_add3_u32 v19, v28, v19, s1
	ds_read2_b32 v[36:37], v6 offset0:165 offset1:173
	v_lshl_add_u64 v[26:27], v[20:21], 0, s[14:15]
	v_and_or_b32 v20, v19, s69, v3
	s_waitcnt lgkmcnt(3)
	v_bfe_u32 v3, v30, 16, 1
	v_add3_u32 v3, v30, v3, s1
	s_waitcnt lgkmcnt(2)
	v_bfe_u32 v19, v32, 16, 1
	ds_read2_b32 v[38:39], v6 offset0:198 offset1:206
	v_lshrrev_b32_e32 v3, 16, v3
	v_add3_u32 v19, v32, v19, s1
	ds_read2_b32 v[40:41], v6 offset0:231 offset1:239
	v_and_or_b32 v21, v19, s69, v3
	s_waitcnt lgkmcnt(3)
	v_bfe_u32 v3, v34, 16, 1
	v_add3_u32 v3, v34, v3, s1
	s_waitcnt lgkmcnt(2)
	v_bfe_u32 v19, v36, 16, 1
	v_lshrrev_b32_e32 v3, 16, v3
	v_add3_u32 v19, v36, v19, s1
	v_and_or_b32 v22, v19, s69, v3
	s_waitcnt lgkmcnt(1)
	v_bfe_u32 v3, v38, 16, 1
	v_add3_u32 v3, v38, v3, s1
	s_waitcnt lgkmcnt(0)
	v_bfe_u32 v19, v40, 16, 1
	v_lshrrev_b32_e32 v3, 16, v3
	v_add3_u32 v19, v40, v19, s1
	v_add_u32_e32 v42, s2, v5
	v_and_or_b32 v23, v19, s69, v3
	v_ashrrev_i32_e32 v43, 31, v42
	v_bfe_u32 v3, v25, 16, 1
	v_lshlrev_b64 v[42:43], 11, v[42:43]
	v_add3_u32 v3, v25, v3, s1
	v_bfe_u32 v19, v29, 16, 1
	v_lshl_add_u64 v[42:43], v[26:27], 0, v[42:43]
	v_lshrrev_b32_e32 v3, 16, v3
	v_add3_u32 v19, v29, v19, s1
	global_store_dwordx4 v[42:43], v[20:23], off
	v_add_u32_e32 v24, s2, v7
	v_ashrrev_i32_e32 v25, 31, v24
	v_and_or_b32 v20, v19, s69, v3
	v_bfe_u32 v3, v31, 16, 1
	v_add3_u32 v3, v31, v3, s1
	v_bfe_u32 v19, v33, 16, 1
	v_lshrrev_b32_e32 v3, 16, v3
	v_add3_u32 v19, v33, v19, s1
	v_and_or_b32 v21, v19, s69, v3
	v_bfe_u32 v3, v35, 16, 1
	v_add3_u32 v3, v35, v3, s1
	v_bfe_u32 v19, v37, 16, 1
	v_lshrrev_b32_e32 v3, 16, v3
	v_add3_u32 v19, v37, v19, s1
	v_and_or_b32 v22, v19, s69, v3
	v_bfe_u32 v3, v39, 16, 1
	v_add3_u32 v3, v39, v3, s1
	v_bfe_u32 v19, v41, 16, 1
	v_lshrrev_b32_e32 v3, 16, v3
	v_add3_u32 v19, v41, v19, s1
	v_lshlrev_b64 v[24:25], 11, v[24:25]
	v_and_or_b32 v23, v19, s69, v3
	ds_read2_b32 v[28:29], v6 offset0:16 offset1:24
	v_lshl_add_u64 v[24:25], v[26:27], 0, v[24:25]
	global_store_dwordx4 v[24:25], v[20:23], off
	ds_read2_b32 v[24:25], v6 offset0:49 offset1:57
	ds_read2_b32 v[30:31], v6 offset0:82 offset1:90
	ds_read2_b32 v[32:33], v6 offset0:115 offset1:123
	s_waitcnt lgkmcnt(3)
	v_bfe_u32 v3, v28, 16, 1
	v_add3_u32 v3, v28, v3, s1
	s_waitcnt lgkmcnt(2)
	v_bfe_u32 v19, v24, 16, 1
	ds_read2_b32 v[34:35], v6 offset0:148 offset1:156
	v_lshrrev_b32_e32 v3, 16, v3
	v_add3_u32 v19, v24, v19, s1
	ds_read2_b32 v[36:37], v6 offset0:181 offset1:189
	v_and_or_b32 v20, v19, s69, v3
	s_waitcnt lgkmcnt(3)
	v_bfe_u32 v3, v30, 16, 1
	v_add3_u32 v3, v30, v3, s1
	s_waitcnt lgkmcnt(2)
	v_bfe_u32 v19, v32, 16, 1
	ds_read2_b32 v[38:39], v6 offset0:214 offset1:222
	v_lshrrev_b32_e32 v3, 16, v3
	v_add3_u32 v19, v32, v19, s1
	ds_read2_b32 v[40:41], v6 offset0:247 offset1:255
	v_and_or_b32 v21, v19, s69, v3
	s_waitcnt lgkmcnt(3)
	v_bfe_u32 v3, v34, 16, 1
	v_add3_u32 v3, v34, v3, s1
	s_waitcnt lgkmcnt(2)
	v_bfe_u32 v19, v36, 16, 1
	v_lshrrev_b32_e32 v3, 16, v3
	v_add3_u32 v19, v36, v19, s1
	v_and_or_b32 v22, v19, s69, v3
	s_waitcnt lgkmcnt(1)
	v_bfe_u32 v3, v38, 16, 1
	v_add3_u32 v3, v38, v3, s1
	s_waitcnt lgkmcnt(0)
	v_bfe_u32 v19, v40, 16, 1
	v_lshrrev_b32_e32 v3, 16, v3
	v_add3_u32 v19, v40, v19, s1
	v_add_u32_e32 v42, s2, v8
	v_and_or_b32 v23, v19, s69, v3
	v_ashrrev_i32_e32 v43, 31, v42
	v_bfe_u32 v3, v29, 16, 1
	v_lshlrev_b64 v[42:43], 11, v[42:43]
	v_add3_u32 v3, v29, v3, s1
	v_bfe_u32 v19, v25, 16, 1
	v_lshl_add_u64 v[42:43], v[26:27], 0, v[42:43]
	v_lshrrev_b32_e32 v3, 16, v3
	v_add3_u32 v19, v25, v19, s1
	global_store_dwordx4 v[42:43], v[20:23], off
	v_add_u32_e32 v24, s2, v9
	v_ashrrev_i32_e32 v25, 31, v24
	v_and_or_b32 v20, v19, s69, v3
	v_bfe_u32 v3, v31, 16, 1
	v_add3_u32 v3, v31, v3, s1
	v_bfe_u32 v19, v33, 16, 1
	v_lshrrev_b32_e32 v3, 16, v3
	v_add3_u32 v19, v33, v19, s1
	v_and_or_b32 v21, v19, s69, v3
	v_bfe_u32 v3, v35, 16, 1
	v_add3_u32 v3, v35, v3, s1
	v_bfe_u32 v19, v37, 16, 1
	v_lshrrev_b32_e32 v3, 16, v3
	v_add3_u32 v19, v37, v19, s1
	v_and_or_b32 v22, v19, s69, v3
	v_bfe_u32 v3, v39, 16, 1
	v_add3_u32 v3, v39, v3, s1
	v_bfe_u32 v19, v41, 16, 1
	v_lshrrev_b32_e32 v3, 16, v3
	v_add3_u32 v19, v41, v19, s1
	v_lshlrev_b64 v[24:25], 11, v[24:25]
	v_and_or_b32 v23, v19, s69, v3
	v_lshl_add_u64 v[24:25], v[26:27], 0, v[24:25]
	global_store_dwordx4 v[24:25], v[20:23], off
	s_waitcnt lgkmcnt(0)
	v_readlane_b32 s43, v250, 18
	v_readlane_b32 s44, v250, 19
	v_readlane_b32 s45, v250, 20
	v_readlane_b32 s46, v250, 21
	v_readlane_b32 s47, v250, 22
	v_readlane_b32 s48, v250, 23
	v_readlane_b32 s49, v250, 24
	v_readlane_b32 s50, v250, 25
	v_readlane_b32 s51, v250, 26
	v_readlane_b32 s52, v250, 27
	v_readlane_b32 s53, v250, 28
